# rstd-table fill at GEMM phase start: three serialized load round trips pipelined into one
# baseline (speedup 1.0000x reference)
.LBB0_609:
	s_and_b64 vcc, exec, s[8:9]
	s_cbranch_vccz .LBB0_638
	v_readlane_b32 s0, v254, 39
	s_cmp_gt_i32 s0, 2
	s_mov_b64 s[8:9], -1
	s_cbranch_scc0 .LBB0_636
	v_readlane_b32 s2, v254, 34
	s_cmpk_gt_i32 s2, 0x2ff
	v_readfirstlane_b32 s14, v162
	v_readlane_b32 s3, v254, 35
	s_cbranch_scc1 .LBB0_635
	v_readlane_b32 s2, v254, 34
	v_readlane_b32 s3, v254, 35
	s_ashr_i32 s3, s2, 31
	v_writelane_b32 v254, s2, 34
	s_movk_i32 s0, 0x600
	v_cmp_gt_i32_e32 vcc, s0, v162
	v_writelane_b32 v254, s3, 35
	s_and_saveexec_b64 s[2:3], vcc
	s_cbranch_execz .LBB0_620
	s_add_i32 s0, 0, 0x20000
	v_and_b32_e32 v0, 0xff, v162
	v_lshl_add_u32 v4, v162, 2, s0
	v_ashrrev_i32_e32 v59, 8, v162
	v_readlane_b32 s6, v254, 34
	v_readlane_b32 s7, v254, 35
	s_nop 3
	s_waitcnt lgkmcnt(0)
	v_mov_b64_e32 v[56:57], s[6:7]
	v_mad_i64_i32 v[56:57], s[6:7], v59, s90, v[56:57]
	s_mov_b64 s[6:7], 0x300
	s_nop 0
	v_cmp_gt_i64_e64 s[46:47], s[6:7], v[56:57]
	s_and_saveexec_b64 s[12:13], s[46:47]
	v_ashrrev_i32_e32 v57, 31, v56
	v_lshrrev_b32_e32 v57, 29, v57
	v_add_u32_e32 v57, v56, v57
	v_ashrrev_i32_e32 v58, 3, v57
	v_and_b32_e32 v57, -8, v57
	v_sub_u32_e32 v56, v56, v57
	v_cmp_gt_i32_e64 s[34:35], 0, v56
	v_mov_b32_e32 v57, 0x60
	v_mov_b32_e32 v59, 0x61
	v_cndmask_b32_e64 v57, v57, v59, s[34:35]
	v_mul_lo_u32 v56, v56, v57
	v_add_u32_e32 v56, v56, v58
	v_mul_hi_i32 v57, v56, s97
	v_lshrrev_b32_e32 v58, 31, v57
	v_ashrrev_i32_e32 v57, 4, v57
	v_add_u32_e32 v57, v57, v58
	v_lshlrev_b32_e32 v58, 3, v57
	v_sub_u32_e32 v59, 64, v58
	v_min_i32_e32 v59, 8, v59
	v_sub_u32_e32 v60, 0, v59
	v_max_i32_e32 v59, v59, v60
	v_cvt_f32_u32_e32 v60, v59
	s_movk_i32 s0, 0x60
	v_mul_lo_u32 v57, v57, s0
	v_sub_u32_e32 v56, v56, v57
	v_rcp_iflag_f32_e32 v60, v60
	v_sub_u32_e32 v61, 0, v56
	v_ashrrev_i32_e32 v57, 31, v56
	v_max_i32_e32 v56, v56, v61
	v_mul_f32_e32 v60, 0x4f7ffffe, v60
	v_cvt_u32_f32_e32 v60, v60
	v_sub_u32_e32 v61, 0, v59
	v_mul_lo_u32 v61, v61, v60
	v_mul_hi_u32 v61, v60, v61
	v_add_u32_e32 v60, v60, v61
	v_mul_hi_u32 v60, v56, v60
	v_mul_lo_u32 v60, v60, v59
	v_sub_u32_e32 v56, v56, v60
	v_sub_u32_e32 v60, v56, v59
	v_cmp_ge_u32_e64 s[34:35], v56, v59
	s_nop 1
	v_cndmask_b32_e64 v56, v56, v60, s[34:35]
	v_sub_u32_e32 v60, v56, v59
	v_cmp_ge_u32_e64 s[34:35], v56, v59
	s_nop 1
	v_cndmask_b32_e64 v56, v56, v60, s[34:35]
	v_xor_b32_e32 v56, v56, v57
	v_sub_u32_e32 v56, v56, v57
	v_add_u32_e32 v58, v58, v56
	v_lshl_or_b32 v56, v58, 8, v0
	v_ashrrev_i32_e32 v57, 31, v56
	v_readlane_b32 s6, v254, 37
	v_lshlrev_b64 v[56:57], 6, v[56:57]
	v_readlane_b32 s7, v254, 38
	s_nop 1
	v_lshl_add_u64 v[56:57], s[6:7], 0, v[56:57]
	global_load_dwordx4 v[60:63], v[56:57], off
	global_load_dwordx4 v[64:67], v[56:57], off offset:16
	global_load_dwordx4 v[68:71], v[56:57], off offset:32
	global_load_dwordx4 v[72:75], v[56:57], off offset:48
	s_or_b64 exec, exec, s[12:13]
	v_ashrrev_i32_e32 v215, 8, v162
	v_add_u32_e32 v215, 2, v215
	v_readlane_b32 s6, v254, 34
	v_readlane_b32 s7, v254, 35
	s_nop 3
	v_mov_b64_e32 v[212:213], s[6:7]
	v_mad_i64_i32 v[212:213], s[6:7], v215, s90, v[212:213]
	s_mov_b64 s[6:7], 0x300
	s_nop 0
	v_cmp_gt_i64_e64 s[48:49], s[6:7], v[212:213]
	s_and_saveexec_b64 s[12:13], s[48:49]
	v_ashrrev_i32_e32 v213, 31, v212
	v_lshrrev_b32_e32 v213, 29, v213
	v_add_u32_e32 v213, v212, v213
	v_ashrrev_i32_e32 v214, 3, v213
	v_and_b32_e32 v213, -8, v213
	v_sub_u32_e32 v212, v212, v213
	v_cmp_gt_i32_e64 s[34:35], 0, v212
	v_mov_b32_e32 v213, 0x60
	v_mov_b32_e32 v215, 0x61
	v_cndmask_b32_e64 v213, v213, v215, s[34:35]
	v_mul_lo_u32 v212, v212, v213
	v_add_u32_e32 v212, v212, v214
	v_mul_hi_i32 v213, v212, s97
	v_lshrrev_b32_e32 v214, 31, v213
	v_ashrrev_i32_e32 v213, 4, v213
	v_add_u32_e32 v213, v213, v214
	v_lshlrev_b32_e32 v214, 3, v213
	v_sub_u32_e32 v215, 64, v214
	v_min_i32_e32 v215, 8, v215
	v_sub_u32_e32 v216, 0, v215
	v_max_i32_e32 v215, v215, v216
	v_cvt_f32_u32_e32 v216, v215
	s_movk_i32 s0, 0x60
	v_mul_lo_u32 v213, v213, s0
	v_sub_u32_e32 v212, v212, v213
	v_rcp_iflag_f32_e32 v216, v216
	v_sub_u32_e32 v217, 0, v212
	v_ashrrev_i32_e32 v213, 31, v212
	v_max_i32_e32 v212, v212, v217
	v_mul_f32_e32 v216, 0x4f7ffffe, v216
	v_cvt_u32_f32_e32 v216, v216
	v_sub_u32_e32 v217, 0, v215
	v_mul_lo_u32 v217, v217, v216
	v_mul_hi_u32 v217, v216, v217
	v_add_u32_e32 v216, v216, v217
	v_mul_hi_u32 v216, v212, v216
	v_mul_lo_u32 v216, v216, v215
	v_sub_u32_e32 v212, v212, v216
	v_sub_u32_e32 v216, v212, v215
	v_cmp_ge_u32_e64 s[34:35], v212, v215
	s_nop 1
	v_cndmask_b32_e64 v212, v212, v216, s[34:35]
	v_sub_u32_e32 v216, v212, v215
	v_cmp_ge_u32_e64 s[34:35], v212, v215
	s_nop 1
	v_cndmask_b32_e64 v212, v212, v216, s[34:35]
	v_xor_b32_e32 v212, v212, v213
	v_sub_u32_e32 v212, v212, v213
	v_add_u32_e32 v214, v214, v212
	v_lshl_or_b32 v212, v214, 8, v0
	v_ashrrev_i32_e32 v213, 31, v212
	v_readlane_b32 s6, v254, 37
	v_lshlrev_b64 v[212:213], 6, v[212:213]
	v_readlane_b32 s7, v254, 38
	s_nop 1
	v_lshl_add_u64 v[212:213], s[6:7], 0, v[212:213]
	global_load_dwordx4 v[216:219], v[212:213], off
	global_load_dwordx4 v[220:223], v[212:213], off offset:16
	global_load_dwordx4 v[224:227], v[212:213], off offset:32
	global_load_dwordx4 v[228:231], v[212:213], off offset:48
	s_or_b64 exec, exec, s[12:13]
	v_ashrrev_i32_e32 v235, 8, v162
	v_add_u32_e32 v235, 4, v235
	v_readlane_b32 s6, v254, 34
	v_readlane_b32 s7, v254, 35
	s_nop 3
	v_mov_b64_e32 v[232:233], s[6:7]
	v_mad_i64_i32 v[232:233], s[6:7], v235, s90, v[232:233]
	s_mov_b64 s[6:7], 0x300
	s_nop 0
	v_cmp_gt_i64_e64 s[50:51], s[6:7], v[232:233]
	s_and_saveexec_b64 s[12:13], s[50:51]
	v_ashrrev_i32_e32 v233, 31, v232
	v_lshrrev_b32_e32 v233, 29, v233
	v_add_u32_e32 v233, v232, v233
	v_ashrrev_i32_e32 v234, 3, v233
	v_and_b32_e32 v233, -8, v233
	v_sub_u32_e32 v232, v232, v233
	v_cmp_gt_i32_e64 s[34:35], 0, v232
	v_mov_b32_e32 v233, 0x60
	v_mov_b32_e32 v235, 0x61
	v_cndmask_b32_e64 v233, v233, v235, s[34:35]
	v_mul_lo_u32 v232, v232, v233
	v_add_u32_e32 v232, v232, v234
	v_mul_hi_i32 v233, v232, s97
	v_lshrrev_b32_e32 v234, 31, v233
	v_ashrrev_i32_e32 v233, 4, v233
	v_add_u32_e32 v233, v233, v234
	v_lshlrev_b32_e32 v234, 3, v233
	v_sub_u32_e32 v235, 64, v234
	v_min_i32_e32 v235, 8, v235
	v_sub_u32_e32 v236, 0, v235
	v_max_i32_e32 v235, v235, v236
	v_cvt_f32_u32_e32 v236, v235
	s_movk_i32 s0, 0x60
	v_mul_lo_u32 v233, v233, s0
	v_sub_u32_e32 v232, v232, v233
	v_rcp_iflag_f32_e32 v236, v236
	v_sub_u32_e32 v237, 0, v232
	v_ashrrev_i32_e32 v233, 31, v232
	v_max_i32_e32 v232, v232, v237
	v_mul_f32_e32 v236, 0x4f7ffffe, v236
	v_cvt_u32_f32_e32 v236, v236
	v_sub_u32_e32 v237, 0, v235
	v_mul_lo_u32 v237, v237, v236
	v_mul_hi_u32 v237, v236, v237
	v_add_u32_e32 v236, v236, v237
	v_mul_hi_u32 v236, v232, v236
	v_mul_lo_u32 v236, v236, v235
	v_sub_u32_e32 v232, v232, v236
	v_sub_u32_e32 v236, v232, v235
	v_cmp_ge_u32_e64 s[34:35], v232, v235
	s_nop 1
	v_cndmask_b32_e64 v232, v232, v236, s[34:35]
	v_sub_u32_e32 v236, v232, v235
	v_cmp_ge_u32_e64 s[34:35], v232, v235
	s_nop 1
	v_cndmask_b32_e64 v232, v232, v236, s[34:35]
	v_xor_b32_e32 v232, v232, v233
	v_sub_u32_e32 v232, v232, v233
	v_add_u32_e32 v234, v234, v232
	v_lshl_or_b32 v232, v234, 8, v0
	v_ashrrev_i32_e32 v233, 31, v232
	v_readlane_b32 s6, v254, 37
	v_lshlrev_b64 v[232:233], 6, v[232:233]
	v_readlane_b32 s7, v254, 38
	s_nop 1
	v_lshl_add_u64 v[232:233], s[6:7], 0, v[232:233]
	global_load_dwordx4 v[236:239], v[232:233], off
	global_load_dwordx4 v[240:243], v[232:233], off offset:16
	global_load_dwordx4 v[244:247], v[232:233], off offset:32
	global_load_dwordx4 v[248:251], v[232:233], off offset:48
	s_or_b64 exec, exec, s[12:13]
	s_waitcnt vmcnt(0)
	s_and_saveexec_b64 s[12:13], s[46:47]
	v_pk_add_f32 v[56:57], v[62:63], v[66:67]
	v_pk_add_f32 v[60:61], v[60:61], v[64:65]
	v_pk_add_f32 v[62:63], v[70:71], v[74:75]
	v_pk_add_f32 v[64:65], v[68:69], v[72:73]
	v_pk_add_f32 v[56:57], v[56:57], v[62:63]
	v_pk_add_f32 v[60:61], v[60:61], v[64:65]
	s_nop 0
	v_pk_mov_b32 v[62:63], v[60:61], v[56:57] op_sel:[1,0]
	v_mov_b32_e32 v61, v57
	v_pk_add_f32 v[56:57], v[62:63], v[60:61]
	s_nop 0
	v_add_f32_e32 v56, v56, v57
	v_fmamk_f32 v56, v56, 0x3a800000, v188
	v_rsq_f32_e32 v56, v56
	ds_write_b32 v4, v56
	s_or_b64 exec, exec, s[12:13]
	s_and_saveexec_b64 s[12:13], s[48:49]
	v_pk_add_f32 v[212:213], v[218:219], v[222:223]
	v_pk_add_f32 v[216:217], v[216:217], v[220:221]
	v_pk_add_f32 v[218:219], v[226:227], v[230:231]
	v_pk_add_f32 v[220:221], v[224:225], v[228:229]
	v_pk_add_f32 v[212:213], v[212:213], v[218:219]
	v_pk_add_f32 v[216:217], v[216:217], v[220:221]
	s_nop 0
	v_pk_mov_b32 v[218:219], v[216:217], v[212:213] op_sel:[1,0]
	v_mov_b32_e32 v217, v213
	v_pk_add_f32 v[212:213], v[218:219], v[216:217]
	s_nop 0
	v_add_f32_e32 v212, v212, v213
	v_fmamk_f32 v212, v212, 0x3a800000, v188
	v_rsq_f32_e32 v212, v212
	ds_write_b32 v4, v212 offset:2048
	s_or_b64 exec, exec, s[12:13]
	s_and_saveexec_b64 s[12:13], s[50:51]
	v_pk_add_f32 v[232:233], v[238:239], v[242:243]
	v_pk_add_f32 v[236:237], v[236:237], v[240:241]
	v_pk_add_f32 v[238:239], v[246:247], v[250:251]
	v_pk_add_f32 v[240:241], v[244:245], v[248:249]
	v_pk_add_f32 v[232:233], v[232:233], v[238:239]
	v_pk_add_f32 v[236:237], v[236:237], v[240:241]
	s_nop 0
	v_pk_mov_b32 v[238:239], v[236:237], v[232:233] op_sel:[1,0]
	v_mov_b32_e32 v237, v233
	v_pk_add_f32 v[232:233], v[238:239], v[236:237]
	s_nop 0
	v_add_f32_e32 v232, v232, v233
	v_fmamk_f32 v232, v232, 0x3a800000, v188
	v_rsq_f32_e32 v232, v232
	ds_write_b32 v4, v232 offset:4096
	s_or_b64 exec, exec, s[12:13]
	s_branch .LBB0_620

.LBB0_795:
	s_and_b64 vcc, exec, s[8:9]
	s_cbranch_vccz .LBB0_985
	s_add_u32 s2, s4, 0x100000
	s_addc_u32 s3, s5, 0
	v_readlane_b32 s60, v254, 34
	s_cmpk_gt_i32 s60, 0x57f
	v_readfirstlane_b32 s16, v162
	v_readlane_b32 s61, v254, 35
	s_cbranch_scc1 .LBB0_819
	s_movk_i32 s0, 0x600
	s_ashr_i32 s61, s60, 31
	v_cmp_gt_i32_e32 vcc, s0, v162
	s_and_saveexec_b64 s[8:9], vcc
	s_cbranch_execz .LBB0_804
	s_add_i32 s0, 0, 0x20000
	v_and_b32_e32 v0, 0xff, v162
	v_lshl_add_u32 v4, v162, 2, s0
	v_ashrrev_i32_e32 v59, 8, v162
	s_waitcnt lgkmcnt(0)
	v_mov_b64_e32 v[56:57], s[60:61]
	v_mad_i64_i32 v[56:57], s[6:7], v59, s90, v[56:57]
	s_mov_b64 s[6:7], 0x580
	s_nop 0
	v_cmp_gt_i64_e64 s[46:47], s[6:7], v[56:57]
	s_and_saveexec_b64 s[14:15], s[46:47]
	v_ashrrev_i32_e32 v57, 31, v56
	v_lshrrev_b32_e32 v57, 29, v57
	v_add_u32_e32 v57, v56, v57
	v_ashrrev_i32_e32 v58, 3, v57
	v_and_b32_e32 v57, -8, v57
	v_sub_u32_e32 v56, v56, v57
	v_cmp_gt_i32_e64 s[34:35], 0, v56
	s_mov_b32 s0, 0x2e8ba2e9
	s_nop 0
	v_cndmask_b32_e64 v57, v203, v204, s[34:35]
	v_mul_lo_u32 v56, v56, v57
	v_add_u32_e32 v56, v56, v58
	v_mul_hi_i32 v57, v56, s0
	v_lshrrev_b32_e32 v58, 31, v57
	v_ashrrev_i32_e32 v57, 5, v57
	v_add_u32_e32 v57, v57, v58
	v_lshlrev_b32_e32 v58, 3, v57
	v_sub_u32_e32 v59, 64, v58
	v_min_i32_e32 v59, 8, v59
	v_sub_u32_e32 v60, 0, v59
	v_max_i32_e32 v59, v59, v60
	v_cvt_f32_u32_e32 v60, v59
	s_movk_i32 s0, 0xb0
	v_mul_lo_u32 v57, v57, s0
	v_sub_u32_e32 v56, v56, v57
	v_rcp_iflag_f32_e32 v60, v60
	v_sub_u32_e32 v61, 0, v56
	v_ashrrev_i32_e32 v57, 31, v56
	v_max_i32_e32 v56, v56, v61
	v_mul_f32_e32 v60, 0x4f7ffffe, v60
	v_cvt_u32_f32_e32 v60, v60
	v_sub_u32_e32 v61, 0, v59
	v_mul_lo_u32 v61, v61, v60
	v_mul_hi_u32 v61, v60, v61
	v_add_u32_e32 v60, v60, v61
	v_mul_hi_u32 v60, v56, v60
	v_mul_lo_u32 v60, v60, v59
	v_sub_u32_e32 v56, v56, v60
	v_sub_u32_e32 v60, v56, v59
	v_cmp_ge_u32_e64 s[34:35], v56, v59
	s_nop 1
	v_cndmask_b32_e64 v56, v56, v60, s[34:35]
	v_sub_u32_e32 v60, v56, v59
	v_cmp_ge_u32_e64 s[34:35], v56, v59
	s_nop 1
	v_cndmask_b32_e64 v56, v56, v60, s[34:35]
	v_xor_b32_e32 v56, v56, v57
	v_sub_u32_e32 v56, v56, v57
	v_add_u32_e32 v58, v58, v56
	v_lshl_or_b32 v56, v58, 8, v0
	v_ashrrev_i32_e32 v57, 31, v56
	v_readlane_b32 s6, v254, 37
	v_lshlrev_b64 v[56:57], 6, v[56:57]
	v_readlane_b32 s7, v254, 38
	s_nop 1
	v_lshl_add_u64 v[56:57], s[6:7], 0, v[56:57]
	global_load_dwordx4 v[60:63], v[56:57], off
	global_load_dwordx4 v[64:67], v[56:57], off offset:16
	global_load_dwordx4 v[68:71], v[56:57], off offset:32
	global_load_dwordx4 v[72:75], v[56:57], off offset:48
	s_or_b64 exec, exec, s[14:15]
	v_ashrrev_i32_e32 v215, 8, v162
	v_add_u32_e32 v215, 2, v215
	v_mov_b64_e32 v[212:213], s[60:61]
	v_mad_i64_i32 v[212:213], s[6:7], v215, s90, v[212:213]
	s_mov_b64 s[6:7], 0x580
	s_nop 0
	v_cmp_gt_i64_e64 s[48:49], s[6:7], v[212:213]
	s_and_saveexec_b64 s[14:15], s[48:49]
	v_ashrrev_i32_e32 v213, 31, v212
	v_lshrrev_b32_e32 v213, 29, v213
	v_add_u32_e32 v213, v212, v213
	v_ashrrev_i32_e32 v214, 3, v213
	v_and_b32_e32 v213, -8, v213
	v_sub_u32_e32 v212, v212, v213
	v_cmp_gt_i32_e64 s[34:35], 0, v212
	s_mov_b32 s0, 0x2e8ba2e9
	s_nop 0
	v_cndmask_b32_e64 v213, v203, v204, s[34:35]
	v_mul_lo_u32 v212, v212, v213
	v_add_u32_e32 v212, v212, v214
	v_mul_hi_i32 v213, v212, s0
	v_lshrrev_b32_e32 v214, 31, v213
	v_ashrrev_i32_e32 v213, 5, v213
	v_add_u32_e32 v213, v213, v214
	v_lshlrev_b32_e32 v214, 3, v213
	v_sub_u32_e32 v215, 64, v214
	v_min_i32_e32 v215, 8, v215
	v_sub_u32_e32 v216, 0, v215
	v_max_i32_e32 v215, v215, v216
	v_cvt_f32_u32_e32 v216, v215
	s_movk_i32 s0, 0xb0
	v_mul_lo_u32 v213, v213, s0
	v_sub_u32_e32 v212, v212, v213
	v_rcp_iflag_f32_e32 v216, v216
	v_sub_u32_e32 v217, 0, v212
	v_ashrrev_i32_e32 v213, 31, v212
	v_max_i32_e32 v212, v212, v217
	v_mul_f32_e32 v216, 0x4f7ffffe, v216
	v_cvt_u32_f32_e32 v216, v216
	v_sub_u32_e32 v217, 0, v215
	v_mul_lo_u32 v217, v217, v216
	v_mul_hi_u32 v217, v216, v217
	v_add_u32_e32 v216, v216, v217
	v_mul_hi_u32 v216, v212, v216
	v_mul_lo_u32 v216, v216, v215
	v_sub_u32_e32 v212, v212, v216
	v_sub_u32_e32 v216, v212, v215
	v_cmp_ge_u32_e64 s[34:35], v212, v215
	s_nop 1
	v_cndmask_b32_e64 v212, v212, v216, s[34:35]
	v_sub_u32_e32 v216, v212, v215
	v_cmp_ge_u32_e64 s[34:35], v212, v215
	s_nop 1
	v_cndmask_b32_e64 v212, v212, v216, s[34:35]
	v_xor_b32_e32 v212, v212, v213
	v_sub_u32_e32 v212, v212, v213
	v_add_u32_e32 v214, v214, v212
	v_lshl_or_b32 v212, v214, 8, v0
	v_ashrrev_i32_e32 v213, 31, v212
	v_readlane_b32 s6, v254, 37
	v_lshlrev_b64 v[212:213], 6, v[212:213]
	v_readlane_b32 s7, v254, 38
	s_nop 1
	v_lshl_add_u64 v[212:213], s[6:7], 0, v[212:213]
	global_load_dwordx4 v[216:219], v[212:213], off
	global_load_dwordx4 v[220:223], v[212:213], off offset:16
	global_load_dwordx4 v[224:227], v[212:213], off offset:32
	global_load_dwordx4 v[228:231], v[212:213], off offset:48
	s_or_b64 exec, exec, s[14:15]
	v_ashrrev_i32_e32 v235, 8, v162
	v_add_u32_e32 v235, 4, v235
	v_mov_b64_e32 v[232:233], s[60:61]
	v_mad_i64_i32 v[232:233], s[6:7], v235, s90, v[232:233]
	s_mov_b64 s[6:7], 0x580
	s_nop 0
	v_cmp_gt_i64_e64 s[50:51], s[6:7], v[232:233]
	s_and_saveexec_b64 s[14:15], s[50:51]
	v_ashrrev_i32_e32 v233, 31, v232
	v_lshrrev_b32_e32 v233, 29, v233
	v_add_u32_e32 v233, v232, v233
	v_ashrrev_i32_e32 v234, 3, v233
	v_and_b32_e32 v233, -8, v233
	v_sub_u32_e32 v232, v232, v233
	v_cmp_gt_i32_e64 s[34:35], 0, v232
	s_mov_b32 s0, 0x2e8ba2e9
	s_nop 0
	v_cndmask_b32_e64 v233, v203, v204, s[34:35]
	v_mul_lo_u32 v232, v232, v233
	v_add_u32_e32 v232, v232, v234
	v_mul_hi_i32 v233, v232, s0
	v_lshrrev_b32_e32 v234, 31, v233
	v_ashrrev_i32_e32 v233, 5, v233
	v_add_u32_e32 v233, v233, v234
	v_lshlrev_b32_e32 v234, 3, v233
	v_sub_u32_e32 v235, 64, v234
	v_min_i32_e32 v235, 8, v235
	v_sub_u32_e32 v236, 0, v235
	v_max_i32_e32 v235, v235, v236
	v_cvt_f32_u32_e32 v236, v235
	s_movk_i32 s0, 0xb0
	v_mul_lo_u32 v233, v233, s0
	v_sub_u32_e32 v232, v232, v233
	v_rcp_iflag_f32_e32 v236, v236
	v_sub_u32_e32 v237, 0, v232
	v_ashrrev_i32_e32 v233, 31, v232
	v_max_i32_e32 v232, v232, v237
	v_mul_f32_e32 v236, 0x4f7ffffe, v236
	v_cvt_u32_f32_e32 v236, v236
	v_sub_u32_e32 v237, 0, v235
	v_mul_lo_u32 v237, v237, v236
	v_mul_hi_u32 v237, v236, v237
	v_add_u32_e32 v236, v236, v237
	v_mul_hi_u32 v236, v232, v236
	v_mul_lo_u32 v236, v236, v235
	v_sub_u32_e32 v232, v232, v236
	v_sub_u32_e32 v236, v232, v235
	v_cmp_ge_u32_e64 s[34:35], v232, v235
	s_nop 1
	v_cndmask_b32_e64 v232, v232, v236, s[34:35]
	v_sub_u32_e32 v236, v232, v235
	v_cmp_ge_u32_e64 s[34:35], v232, v235
	s_nop 1
	v_cndmask_b32_e64 v232, v232, v236, s[34:35]
	v_xor_b32_e32 v232, v232, v233
	v_sub_u32_e32 v232, v232, v233
	v_add_u32_e32 v234, v234, v232
	v_lshl_or_b32 v232, v234, 8, v0
	v_ashrrev_i32_e32 v233, 31, v232
	v_readlane_b32 s6, v254, 37
	v_lshlrev_b64 v[232:233], 6, v[232:233]
	v_readlane_b32 s7, v254, 38
	s_nop 1
	v_lshl_add_u64 v[232:233], s[6:7], 0, v[232:233]
	global_load_dwordx4 v[236:239], v[232:233], off
	global_load_dwordx4 v[240:243], v[232:233], off offset:16
	global_load_dwordx4 v[244:247], v[232:233], off offset:32
	global_load_dwordx4 v[248:251], v[232:233], off offset:48
	s_or_b64 exec, exec, s[14:15]
	s_waitcnt vmcnt(0)
	s_and_saveexec_b64 s[14:15], s[46:47]
	v_pk_add_f32 v[56:57], v[62:63], v[66:67]
	v_pk_add_f32 v[60:61], v[60:61], v[64:65]
	v_pk_add_f32 v[62:63], v[70:71], v[74:75]
	v_pk_add_f32 v[64:65], v[68:69], v[72:73]
	v_pk_add_f32 v[56:57], v[56:57], v[62:63]
	v_pk_add_f32 v[60:61], v[60:61], v[64:65]
	s_nop 0
	v_pk_mov_b32 v[62:63], v[60:61], v[56:57] op_sel:[1,0]
	v_mov_b32_e32 v61, v57
	v_pk_add_f32 v[56:57], v[62:63], v[60:61]
	s_nop 0
	v_add_f32_e32 v56, v56, v57
	v_fmamk_f32 v56, v56, 0x3a800000, v188
	v_rsq_f32_e32 v56, v56
	ds_write_b32 v4, v56
	s_or_b64 exec, exec, s[14:15]
	s_and_saveexec_b64 s[14:15], s[48:49]
	v_pk_add_f32 v[212:213], v[218:219], v[222:223]
	v_pk_add_f32 v[216:217], v[216:217], v[220:221]
	v_pk_add_f32 v[218:219], v[226:227], v[230:231]
	v_pk_add_f32 v[220:221], v[224:225], v[228:229]
	v_pk_add_f32 v[212:213], v[212:213], v[218:219]
	v_pk_add_f32 v[216:217], v[216:217], v[220:221]
	s_nop 0
	v_pk_mov_b32 v[218:219], v[216:217], v[212:213] op_sel:[1,0]
	v_mov_b32_e32 v217, v213
	v_pk_add_f32 v[212:213], v[218:219], v[216:217]
	s_nop 0
	v_add_f32_e32 v212, v212, v213
	v_fmamk_f32 v212, v212, 0x3a800000, v188
	v_rsq_f32_e32 v212, v212
	ds_write_b32 v4, v212 offset:2048
	s_or_b64 exec, exec, s[14:15]
	s_and_saveexec_b64 s[14:15], s[50:51]
	v_pk_add_f32 v[232:233], v[238:239], v[242:243]
	v_pk_add_f32 v[236:237], v[236:237], v[240:241]
	v_pk_add_f32 v[238:239], v[246:247], v[250:251]
	v_pk_add_f32 v[240:241], v[244:245], v[248:249]
	v_pk_add_f32 v[232:233], v[232:233], v[238:239]
	v_pk_add_f32 v[236:237], v[236:237], v[240:241]
	s_nop 0
	v_pk_mov_b32 v[238:239], v[236:237], v[232:233] op_sel:[1,0]
	v_mov_b32_e32 v237, v233
	v_pk_add_f32 v[232:233], v[238:239], v[236:237]
	s_nop 0
	v_add_f32_e32 v232, v232, v233
	v_fmamk_f32 v232, v232, 0x3a800000, v188
	v_rsq_f32_e32 v232, v232
	ds_write_b32 v4, v232 offset:4096
	s_or_b64 exec, exec, s[14:15]
